# scan loader waves run their short LDS write phase at the scan waves' priority (s_setprio 3 .. 0) so the refill finishes in one burst
# speedup vs baseline: 1.0074x; 1.0038x over previous
; #define LAS __attribute__((address_space(3)))
; __device__ __forceinline__ void scan_load_chunk(LAS unsigned char* slot, const float* Wd, const float* V, const bf16_t* RKKB, int p, int rg, int s0, int lt) {
;     ...
;     if (lt < 128) { const int st = lt >> 2, hf = lt & 3; *(LAS u32x4*)(slot + st * SCAN_STEP_B + 1280 + hf * 16) = r[6]; }
.LBB0_343:
	s_or_b64 exec, exec, s[18:19]
	s_setprio 0

; #define LAS __attribute__((address_space(3)))
; __device__ __forceinline__ void scan_load_chunk(LAS unsigned char* slot, const float* Wd, const float* V, const bf16_t* RKKB, int p, int rg, int s0, int lt) {
;     ...
;     for (int j = 0; j < 2; ++j) { const int idx = lt + 256 * j, st = idx >> 4, part = idx & 15; *(LAS u32x4*)(slot + st * SCAN_STEP_B + part * 16) = r[j]; }
; #pragma unroll
;     for (int j = 2; j < 6; ++j) { const int k = lt + 256 * (j - 2), st = k >> 5, rem = k & 31, q = rem >> 3, part = rem & 7; const u32x4 w = r[j];
;         const int Q = (q == 0) ? 4 : (q == 1) ? 2 : (q == 2) ? 3 : 1;
;         LAS f32x4* d = (LAS f32x4*)(slot + st * SCAN_STEP_B + Q * 256 + part * 32);
.LBB0_348:
	s_andn2_b64 vcc, exec, s[18:19]
	s_cbranch_vccnz .LBB0_345
	s_cmpk_gt_u32 s22, 0x7d
	s_cbranch_scc1 .LBB0_344
	s_setprio 3
	s_add_i32 s18, s22, 2
	s_mul_i32 s19, s18, 0xab
	s_bfe_u32 s19, s19, 0x70009
	s_mul_i32 s19, s19, 3
	s_sub_i32 s18, s18, s19
	s_and_b32 s18, s18, 0xff
	s_mul_i32 s18, s18, 0xa800
	s_add_i32 s23, s18, 0
	v_add_u32_e32 v0, s23, v73
	v_add_u32_e32 v34, v0, v74
	v_add_u32_e32 v0, v0, v75
	s_waitcnt vmcnt(0)
	ds_write_b128 v34, v[130:133]
	ds_write_b128 v0, v[126:129]
	v_cmp_lt_i32_e32 vcc, 0, v69
	v_mov_b32_e32 v0, 0x400
	s_and_saveexec_b64 s[18:19], vcc
	s_cbranch_execz .LBB0_356
	v_cmp_ne_u32_e32 vcc, 1, v69
	s_and_saveexec_b64 s[20:21], vcc
	s_xor_b64 s[20:21], exec, s[20:21]
	s_or_saveexec_b64 s[20:21], s[20:21]
	v_mov_b32_e32 v0, v70
	s_xor_b64 exec, exec, s[20:21]
	v_mov_b32_e32 v0, 0x200
	s_or_b64 exec, exec, s[20:21]
